# attention: SIMD-partner stagger: waves 4-7 enter each unit's tile loop ~1300 cycles (s_sleep 20) after waves 0-3; on top of v52
# baseline (speedup 1.0000x reference)
; #define LAS __attribute__((address_space(3)))
;     __device__ __forceinline__ int lane_() const { return hw_lane(); }
; __device__ __forceinline__ void softmax_step(f32x16& p0, f32x16& p1, float& m, float& l, f32x16 (&o)[2], u32x4 (&pw)[4]) {
;     ...
;     float sa = 0.f, sb = 0.f;
; #pragma unroll
;     for (int r = 0; r < 16; ++r) { p0[r] = __builtin_amdgcn_exp2f(p0[r]); p1[r] = __builtin_amdgcn_exp2f(p1[r]); sa += p0[r]; sb += p1[r]; }
;     l += sa + sb;
; __device__ __forceinline__ void attn_unit(Frame& F, const Ptrs& P, int u, int u_next, bf16x8 (&qa)[4], ScanRider& R) {
;     ...
;     int lane = F.lane_(); asm volatile("" : "+v"(lane));
;     const int b = u >> 8, nb = u & 63, kvh = (u >> 6) & 3;
;     const int wid = F.wave, r32 = lane & 31, hi = lane >> 5;
;     LAS unsigned char* lds = F.lds;
;     const int hq = kvh * 4 + (wid >> 1), jlo = wid & 1, r0 = 64 * jlo;
;     const size_t qrow = (size_t)b * SEQ + nb * 128 + r0;
;     bf16* Qw = (bf16*)(P.ws + WS_YG) + (qrow + r32) * 2048 + 1024 + hq * 64;
;     const bf16* Gb = (const bf16*)(P.ws + WS_G); float* SSQ = (float*)(P.ws + WS_SSQ);
;     LAS bf16x8* qbl = (LAS bf16x8*)(lds + LDS_QB + wid * 4096) + lane;
;     const float sinkl = P.sink[hq] * LOG2E;
;     const LAS unsigned char* vb0 = lds + LDS_V + ((lane >> 4) & 1) * 32 + (lane & 3) * 8 + (4 * hi + ((lane & 15) >> 2)) * 64;
;     asm volatile("s_waitcnt vmcnt(0)" ::: "memory");
;     __syncthreads();
;     const int kmin = nb == 0 ? 128 : 0, kmax = nb == 63 ? 255 : 383;
;     const bool edge_all = (nb == 0 || nb == 63);
;     float mA = sinkl, mB = sinkl, lA = hi == 0 ? 1.f : 0.f, lB = lA;
;     f32x16 oA[2], oB[2]; oA[0] = f32x16{}; oA[1] = f32x16{}; oB[0] = f32x16{}; oB[1] = f32x16{};
; #pragma unroll 1
.LBB0_649:
	s_lshr_b32 s2, s80, 4
	s_and_b32 s79, s2, 12
	s_add_i32 s79, s79, s42
	s_lshl_b32 s2, s79, 2
	v_mbcnt_lo_u32_b32 v80, -1, 0
	v_mbcnt_hi_u32_b32 v80, -1, v80
	v_mov_b32_e32 v0, s2
	global_load_dword v81, v0, s[44:45]
	v_mov_b32_e32 v14, v1
	v_mov_b32_e32 v15, v1
	s_mov_b32 s6, s80
	v_mov_b32_e32 v0, v1
	v_mov_b32_e32 v2, v1
	v_mov_b32_e32 v3, v1
	v_mov_b32_e32 v4, v1
	v_mov_b32_e32 v5, v1
	v_mov_b32_e32 v6, v1
	v_mov_b32_e32 v7, v1
	v_mov_b32_e32 v8, v1
	v_mov_b32_e32 v9, v1
	v_mov_b32_e32 v10, v1
	v_mov_b32_e32 v11, v1
	v_mov_b32_e32 v12, v1
	v_mov_b32_e32 v13, v1
	v_mov_b64_e32 v[46:47], v[14:15]
	v_mov_b64_e32 v[30:31], v[14:15]
	v_mov_b64_e32 v[78:79], v[14:15]
	v_mov_b64_e32 v[62:63], v[14:15]
	s_and_b32 s81, s6, 63
	v_mov_b64_e32 v[44:45], v[12:13]
	v_mov_b64_e32 v[42:43], v[10:11]
	v_mov_b64_e32 v[40:41], v[8:9]
	v_mov_b64_e32 v[38:39], v[6:7]
	v_mov_b64_e32 v[36:37], v[4:5]
	v_mov_b64_e32 v[34:35], v[2:3]
	v_mov_b64_e32 v[32:33], v[0:1]
	v_mov_b64_e32 v[28:29], v[12:13]
	v_mov_b64_e32 v[26:27], v[10:11]
	v_mov_b64_e32 v[24:25], v[8:9]
	v_mov_b64_e32 v[22:23], v[6:7]
	v_mov_b64_e32 v[20:21], v[4:5]
	v_mov_b64_e32 v[18:19], v[2:3]
	v_mov_b64_e32 v[16:17], v[0:1]
	v_mov_b64_e32 v[76:77], v[12:13]
	v_mov_b64_e32 v[74:75], v[10:11]
	v_mov_b64_e32 v[72:73], v[8:9]
	v_mov_b64_e32 v[70:71], v[6:7]
	v_mov_b64_e32 v[68:69], v[4:5]
	v_mov_b64_e32 v[66:67], v[2:3]
	v_mov_b64_e32 v[64:65], v[0:1]
	v_mov_b64_e32 v[60:61], v[12:13]
	v_mov_b64_e32 v[58:59], v[10:11]
	v_mov_b64_e32 v[56:57], v[8:9]
	v_mov_b64_e32 v[54:55], v[6:7]
	v_mov_b64_e32 v[52:53], v[4:5]
	v_mov_b64_e32 v[50:51], v[2:3]
	v_mov_b64_e32 v[48:49], v[0:1]
	v_lshlrev_b32_e32 v0, 4, v80
	v_and_b32_e32 v177, 31, v80
	v_ashrrev_i32_e32 v14, 5, v80
	v_lshlrev_b32_e32 v2, 1, v80
	v_lshlrev_b32_e32 v3, 3, v80
	v_add_u32_e32 v15, s30, v0
	v_and_b32_e32 v0, 0xc0, v0
	s_cmp_eq_u32 s81, 0
	v_cmp_gt_u32_e64 s[2:3], 32, v80
	v_and_b32_e32 v2, 32, v2
	v_and_b32_e32 v4, 24, v3
	v_add_u32_e32 v185, s43, v3
	v_lshlrev_b32_e32 v3, 10, v14
	v_lshlrev_b32_e32 v5, 4, v177
	v_or_b32_e32 v6, s14, v177
	v_lshl_or_b32 v0, v14, 8, v0
	s_waitcnt vmcnt(0)
	s_cselect_b32 s4, 0x80, 0
	s_cmp_eq_u32 s81, 63
	s_movk_i32 s5, 0x17f
	v_cndmask_b32_e64 v173, 0, 1.0, s[2:3]
	v_add3_u32 v195, 0, v3, v5
	v_or_b32_e32 v3, 0x100, v6
	v_or_b32_e32 v5, 32, v6
	v_or_b32_e32 v7, 0x120, v6
	v_or3_b32 v0, v0, v2, v4
	s_cselect_b32 s5, 0xff, s5
	s_mov_b32 s80, 0
	s_mov_b32 s82, 0
	v_lshl_add_u32 v189, v14, 2, s14
	s_waitcnt vmcnt(0)
	v_mul_f32_e32 v201, 0x3fb8aa3b, v81
	v_add_u32_e32 v196, 0, v0
	v_max_u32_e32 v197, s4, v6
	v_max_u32_e32 v198, s4, v5
	v_min_u32_e32 v199, s5, v3
	v_min_u32_e32 v200, s5, v7
	v_mov_b32_e32 v181, v173
	v_mov_b32_e32 v202, v201
	s_barrier
	s_cmp_eq_u64 s[16:17], 0
	s_cbranch_scc1 .Lattn_stag
	s_sleep 20
.Lattn_stag:
	s_branch .LBB0_651
.LBB0_650:
	v_add_f32_e32 v0, 0, v208
	v_add_f32_e32 v2, 0, v108
	v_add_f32_e32 v0, v207, v0
	v_add_f32_e32 v2, v107, v2
	v_add_f32_e32 v0, v98, v0
	v_add_f32_e32 v2, v82, v2
	v_add_f32_e32 v0, v97, v0
	v_add_f32_e32 v2, v81, v2
	v_add_f32_e32 v0, v96, v0
	v_add_f32_e32 v2, v80, v2
	v_add_f32_e32 v0, v210, v0
	v_add_f32_e32 v2, v85, v2
	v_add_f32_e32 v0, v209, v0
	v_add_f32_e32 v2, v84, v2
	v_add_f32_e32 v0, v101, v0
	v_add_f32_e32 v2, v83, v2
	v_add_f32_e32 v0, v211, v0
	v_add_f32_e32 v2, v109, v2
	v_add_f32_e32 v0, v105, v0
	v_add_f32_e32 v2, v89, v2
	v_add_f32_e32 v0, v104, v0
	v_add_f32_e32 v2, v88, v2
	v_add_f32_e32 v0, v103, v0
	v_add_f32_e32 v2, v87, v2
	v_add_f32_e32 v0, v102, v0
	v_add_f32_e32 v2, v86, v2
	v_add_f32_e32 v0, v100, v0
	v_add_f32_e32 v2, v92, v2
	v_add_f32_e32 v0, v99, v0
	v_add_f32_e32 v2, v91, v2
	v_add_f32_e32 v0, v106, v0
	v_add_f32_e32 v2, v90, v2
	v_add_f32_e32 v0, v2, v0
	v_add_f32_e32 v173, v173, v0
	v_add_f32_e32 v0, 0, v128
	v_add_f32_e32 v2, 0, v203
	v_add_f32_e32 v0, v129, v0
	v_add_f32_e32 v2, v204, v2
	v_add_f32_e32 v0, v130, v0
	v_add_f32_e32 v2, v205, v2
	v_add_f32_e32 v0, v131, v0
	v_add_f32_e32 v2, v206, v2
	v_add_f32_e32 v0, v132, v0
	v_add_f32_e32 v2, v116, v2
	v_add_f32_e32 v0, v133, v0
	v_add_f32_e32 v2, v117, v2
	v_add_f32_e32 v0, v134, v0
	v_add_f32_e32 v2, v118, v2
	v_add_f32_e32 v0, v135, v0
	v_add_f32_e32 v2, v119, v2
	v_add_f32_e32 v0, v136, v0
	v_add_f32_e32 v2, v120, v2
	v_add_f32_e32 v0, v137, v0
	v_add_f32_e32 v2, v121, v2
	v_add_f32_e32 v0, v138, v0
	v_add_f32_e32 v2, v122, v2
	v_add_f32_e32 v0, v139, v0
	v_add_f32_e32 v2, v123, v2
	v_add_f32_e32 v0, v140, v0
	v_add_f32_e32 v2, v124, v2
	v_add_f32_e32 v0, v141, v0
	v_add_f32_e32 v2, v125, v2
	v_add_f32_e32 v0, v142, v0
	v_add_f32_e32 v2, v126, v2
	v_add_f32_e32 v0, v143, v0
	v_add_f32_e32 v2, v127, v2
	v_add_f32_e32 v0, v2, v0
	s_add_i32 s82, s82, 1
	s_add_i32 s80, s80, 64
	v_add_f32_e32 v181, v181, v0
	v_add_u32_e32 v196, 0x2000, v196
	s_cmpk_eq_i32 s80, 0x140
	v_add_u32_e32 v195, 0x2000, v195
	s_cbranch_scc1 .LBB0_670
